# K=2 + early invalidate in both barrier paths (leader: right after its L2 writeback; tail wait removed)
# baseline (speedup 1.0000x reference)
.LBB0_273:
	s_andn2_saveexec_b64 s[6:7], s[6:7]
	s_cbranch_execz .LBB0_291
	s_mov_b64 s[6:7], exec
	buffer_wbl2 sc1
	s_waitcnt lgkmcnt(0)
	s_waitcnt vmcnt(0)
	buffer_inv sc1
	v_mbcnt_lo_u32_b32 v3, s6, 0
	v_mbcnt_hi_u32_b32 v3, s7, v3
	v_cmp_eq_u32_e32 vcc, 0, v3
	s_and_saveexec_b64 s[10:11], vcc
	s_cbranch_execz .LBB0_276
	s_bcnt1_i32_b64 s6, s[6:7]
	v_mov_b32_e32 v4, 0x3000
	v_mov_b32_e32 v5, s6
	global_atomic_add v4, v4, v5, s[78:79] offset:1024 sc0

.LBB0_290:
	s_or_b64 exec, exec, s[6:7]
	v_mov_b32_e32 v2, 0x2000
	v_mov_b32_e32 v3, 1
	s_waitcnt vmcnt(0)
	global_atomic_add v2, v3, s[4:5] offset:1024

.LBB0_368:
	s_andn2_saveexec_b64 s[6:7], s[6:7]
	s_cbranch_execz .LBB0_386
	s_mov_b64 s[6:7], exec
	buffer_wbl2 sc1
	s_waitcnt lgkmcnt(0)
	s_waitcnt vmcnt(0)
	buffer_inv sc1
	v_mbcnt_lo_u32_b32 v3, s6, 0
	v_mbcnt_hi_u32_b32 v3, s7, v3
	v_cmp_eq_u32_e32 vcc, 0, v3
	s_and_saveexec_b64 s[8:9], vcc
	s_cbranch_execz .LBB0_371
	s_bcnt1_i32_b64 s6, s[6:7]
	v_mov_b32_e32 v4, 0x3000
	v_mov_b32_e32 v5, s6
	global_atomic_add v4, v4, v5, s[78:79] offset:1024 sc0
